# norm phase split-K fold: two loads in flight (each load issued before the previous is drained and added; odd loads land in v[248:251]) on the 5 regular 9-load blocks
# baseline (speedup 1.0000x reference)
.LBB0_92:
	v_ashrrev_i32_e32 v33, 31, v32
	v_lshlrev_b64 v[32:33], 13, v[32:33]
	v_lshl_add_u64 v[32:33], s[12:13], 0, v[32:33]
	v_lshl_add_u64 v[34:35], v[32:33], 0, v[174:175]
	global_load_dwordx4 v[96:99], v[192:193], off
	global_load_dwordx4 v[60:63], v[190:191], off
	global_load_dwordx4 v[112:115], v[34:35], off
	global_load_dwordx4 v[104:107], v[34:35], off offset:1024
	global_load_dwordx4 v[88:91], v[196:197], off
	global_load_dwordx4 v[56:59], v[194:195], off
	global_load_dwordx4 v[80:83], v[200:201], off
	global_load_dwordx4 v[52:55], v[198:199], off
	global_load_dwordx4 v[108:111], v[34:35], off offset:2048
	global_load_dwordx4 v[100:103], v[34:35], off offset:3072
	global_load_dwordx4 v[76:79], v[204:205], off
	global_load_dwordx4 v[48:51], v[202:203], off
	v_mov_b32_e32 v165, v175
	v_mov_b32_e32 v167, v175
	v_lshl_add_u64 v[34:35], v[32:33], 0, v[164:165]
	v_lshl_add_u64 v[36:37], v[32:33], 0, v[166:167]
	v_mov_b32_e32 v169, v175
	v_mov_b32_e32 v171, v175
	global_load_dwordx4 v[72:75], v[208:209], off
	global_load_dwordx4 v[44:47], v[206:207], off
	global_load_dwordx4 v[120:123], v[34:35], off
	global_load_dwordx4 v[116:119], v[36:37], off
	global_load_dwordx4 v[68:71], v[212:213], off
	s_nop 0
	global_load_dwordx4 v[36:39], v[210:211], off
	v_lshl_add_u64 v[34:35], v[32:33], 0, v[168:169]
	v_lshl_add_u64 v[32:33], v[32:33], 0, v[170:171]
	global_load_dwordx4 v[128:131], v[34:35], off
	global_load_dwordx4 v[124:127], v[32:33], off
	global_load_dwordx4 v[84:87], v[216:217], off
	global_load_dwordx4 v[40:43], v[214:215], off
	global_load_dwordx4 v[64:67], v[220:221], off
	s_nop 0
	global_load_dwordx4 v[32:35], v[218:219], off
	s_and_b64 vcc, exec, s[24:25]
	s_cbranch_vccz .LBB0_94
	v_ashrrev_i32_e32 v235, 31, v234
	v_lshlrev_b64 v[92:93], 13, v[234:235]
	v_lshl_add_u64 v[156:157], s[8:9], 0, v[92:93]
	v_lshl_add_u64 v[144:145], v[156:157], 0, v[174:175]
	global_load_dwordx4 v[92:95], v[144:145], off
	v_add_co_u32_e32 v142, vcc, 0x800000, v144
	s_mov_b32 s1, 0x801000
	s_nop 0
	v_addc_co_u32_e32 v143, vcc, 0, v145, vcc
	v_add_co_u32_e32 v148, vcc, 0x1000000, v144
	s_nop 1
	v_addc_co_u32_e32 v149, vcc, 0, v145, vcc
	v_add_co_u32_e32 v152, vcc, 0x1800000, v144
	global_load_dwordx4 v[248:251], v[142:143], off
	s_waitcnt vmcnt(1)
	v_pk_add_f32 v[132:133], v[94:95], 0 op_sel_hi:[1,0]
	v_pk_add_f32 v[134:135], v[92:93], 0 op_sel_hi:[1,0]
	v_addc_co_u32_e32 v153, vcc, 0, v145, vcc
	v_add_co_u32_e32 v154, vcc, 0x2000000, v144
	global_load_dwordx4 v[92:95], v[148:149], off
	s_waitcnt vmcnt(1)
	v_pk_add_f32 v[132:133], v[132:133], v[250:251]
	v_pk_add_f32 v[134:135], v[134:135], v[248:249]
	v_addc_co_u32_e32 v155, vcc, 0, v145, vcc
	v_add_co_u32_e32 v150, vcc, 0x2800000, v144
	global_load_dwordx4 v[248:251], v[152:153], off
	s_waitcnt vmcnt(1)
	v_pk_add_f32 v[132:133], v[132:133], v[94:95]
	v_pk_add_f32 v[134:135], v[134:135], v[92:93]
	v_addc_co_u32_e32 v151, vcc, 0, v145, vcc
	v_add_co_u32_e32 v146, vcc, 0x3000000, v144
	global_load_dwordx4 v[92:95], v[154:155], off
	s_waitcnt vmcnt(1)
	v_pk_add_f32 v[132:133], v[132:133], v[250:251]
	v_pk_add_f32 v[134:135], v[134:135], v[248:249]
	v_addc_co_u32_e32 v147, vcc, 0, v145, vcc
	v_add_co_u32_e32 v140, vcc, 0x3800000, v144
	global_load_dwordx4 v[248:251], v[150:151], off
	s_waitcnt vmcnt(1)
	v_pk_add_f32 v[132:133], v[132:133], v[94:95]
	v_pk_add_f32 v[134:135], v[134:135], v[92:93]
	v_addc_co_u32_e32 v141, vcc, 0, v145, vcc
	global_load_dwordx4 v[92:95], v[146:147], off
	s_waitcnt vmcnt(1)
	v_pk_add_f32 v[132:133], v[132:133], v[250:251]
	v_pk_add_f32 v[134:135], v[134:135], v[248:249]
	global_load_dwordx4 v[248:251], v[140:141], off
	s_waitcnt vmcnt(1)
	v_pk_add_f32 v[132:133], v[132:133], v[94:95]
	v_pk_add_f32 v[134:135], v[134:135], v[92:93]
	global_load_dwordx4 v[92:95], v[222:223], off
	s_waitcnt vmcnt(1)
	v_pk_add_f32 v[132:133], v[132:133], v[250:251]
	v_pk_add_f32 v[134:135], v[134:135], v[248:249]
	s_waitcnt vmcnt(0)
	v_pk_fma_f32 v[94:95], v[132:133], v[94:95], v[114:115]
	v_pk_fma_f32 v[92:93], v[134:135], v[92:93], v[112:113]
	global_load_dwordx4 v[132:135], v[144:145], off offset:1024
	global_load_dwordx4 v[248:251], v[142:143], off offset:1024
	s_waitcnt vmcnt(1)
	v_pk_add_f32 v[136:137], v[134:135], 0 op_sel_hi:[1,0]
	v_pk_add_f32 v[138:139], v[132:133], 0 op_sel_hi:[1,0]
	global_load_dwordx4 v[132:135], v[148:149], off offset:1024
	s_waitcnt vmcnt(1)
	v_pk_add_f32 v[136:137], v[136:137], v[250:251]
	v_pk_add_f32 v[138:139], v[138:139], v[248:249]
	global_load_dwordx4 v[248:251], v[152:153], off offset:1024
	s_waitcnt vmcnt(1)
	v_pk_add_f32 v[136:137], v[136:137], v[134:135]
	v_pk_add_f32 v[138:139], v[138:139], v[132:133]
	global_load_dwordx4 v[132:135], v[154:155], off offset:1024
	s_waitcnt vmcnt(1)
	v_pk_add_f32 v[136:137], v[136:137], v[250:251]
	v_pk_add_f32 v[138:139], v[138:139], v[248:249]
	global_load_dwordx4 v[248:251], v[150:151], off offset:1024
	s_waitcnt vmcnt(1)
	v_pk_add_f32 v[136:137], v[136:137], v[134:135]
	v_pk_add_f32 v[138:139], v[138:139], v[132:133]
	global_load_dwordx4 v[132:135], v[146:147], off offset:1024
	s_waitcnt vmcnt(1)
	v_pk_add_f32 v[136:137], v[136:137], v[250:251]
	v_pk_add_f32 v[138:139], v[138:139], v[248:249]
	global_load_dwordx4 v[248:251], v[140:141], off offset:1024
	s_waitcnt vmcnt(1)
	v_pk_add_f32 v[136:137], v[136:137], v[134:135]
	v_pk_add_f32 v[138:139], v[138:139], v[132:133]
	global_load_dwordx4 v[132:135], v[224:225], off
	s_waitcnt vmcnt(1)
	v_pk_add_f32 v[136:137], v[136:137], v[250:251]
	v_pk_add_f32 v[138:139], v[138:139], v[248:249]
	s_waitcnt vmcnt(0)
	v_pk_fma_f32 v[134:135], v[136:137], v[134:135], v[106:107]
	v_pk_fma_f32 v[132:133], v[138:139], v[132:133], v[104:105]
	global_load_dwordx4 v[136:139], v[144:145], off offset:2048
	global_load_dwordx4 v[248:251], v[142:143], off offset:2048
	s_waitcnt vmcnt(1)
	v_pk_add_f32 v[158:159], v[138:139], 0 op_sel_hi:[1,0]
	v_pk_add_f32 v[160:161], v[136:137], 0 op_sel_hi:[1,0]
	global_load_dwordx4 v[136:139], v[148:149], off offset:2048
	s_waitcnt vmcnt(1)
	v_pk_add_f32 v[158:159], v[158:159], v[250:251]
	v_pk_add_f32 v[160:161], v[160:161], v[248:249]
	global_load_dwordx4 v[248:251], v[152:153], off offset:2048
	s_waitcnt vmcnt(1)
	v_pk_add_f32 v[158:159], v[158:159], v[138:139]
	v_pk_add_f32 v[160:161], v[160:161], v[136:137]
	global_load_dwordx4 v[136:139], v[154:155], off offset:2048
	s_waitcnt vmcnt(1)
	v_pk_add_f32 v[158:159], v[158:159], v[250:251]
	v_pk_add_f32 v[160:161], v[160:161], v[248:249]
	global_load_dwordx4 v[248:251], v[150:151], off offset:2048
	s_waitcnt vmcnt(1)
	v_pk_add_f32 v[158:159], v[158:159], v[138:139]
	v_pk_add_f32 v[160:161], v[160:161], v[136:137]
	global_load_dwordx4 v[136:139], v[146:147], off offset:2048
	s_waitcnt vmcnt(1)
	v_pk_add_f32 v[158:159], v[158:159], v[250:251]
	v_pk_add_f32 v[160:161], v[160:161], v[248:249]
	global_load_dwordx4 v[248:251], v[140:141], off offset:2048
	s_waitcnt vmcnt(1)
	v_pk_add_f32 v[158:159], v[158:159], v[138:139]
	v_pk_add_f32 v[160:161], v[160:161], v[136:137]
	global_load_dwordx4 v[136:139], v[226:227], off
	s_waitcnt vmcnt(1)
	v_pk_add_f32 v[158:159], v[158:159], v[250:251]
	v_pk_add_f32 v[160:161], v[160:161], v[248:249]
	s_waitcnt vmcnt(0)
	v_pk_fma_f32 v[138:139], v[158:159], v[138:139], v[110:111]
	v_pk_fma_f32 v[136:137], v[160:161], v[136:137], v[108:109]
	global_load_dwordx4 v[158:161], v[144:145], off offset:3072
	s_waitcnt vmcnt(0)
	v_pk_add_f32 v[162:163], v[160:161], 0 op_sel_hi:[1,0]
	v_pk_add_f32 v[180:181], v[158:159], 0 op_sel_hi:[1,0]
	global_load_dwordx4 v[158:161], v[142:143], off offset:3072
	s_waitcnt vmcnt(0)
	v_pk_add_f32 v[142:143], v[162:163], v[160:161]
	v_pk_add_f32 v[162:163], v[180:181], v[158:159]
	global_load_dwordx4 v[158:161], v[148:149], off offset:3072
	s_waitcnt vmcnt(0)
	v_pk_add_f32 v[142:143], v[142:143], v[160:161]
	v_pk_add_f32 v[148:149], v[162:163], v[158:159]
	global_load_dwordx4 v[158:161], v[152:153], off offset:3072
	s_waitcnt vmcnt(0)
	v_pk_add_f32 v[148:149], v[148:149], v[158:159]
	v_pk_add_f32 v[142:143], v[142:143], v[160:161]
	global_load_dwordx4 v[152:155], v[154:155], off offset:3072
	v_add_co_u32_e32 v158, vcc, s1, v144
	s_mov_b32 s1, 0x1001000
	s_nop 0
	v_addc_co_u32_e32 v159, vcc, 0, v145, vcc
	v_add_co_u32_e32 v160, vcc, s1, v144
	s_mov_b32 s1, 0x1801000
	s_nop 0
	v_addc_co_u32_e32 v161, vcc, 0, v145, vcc
	v_add_co_u32_e32 v162, vcc, s1, v144
	s_mov_b32 s1, 0x2001000
	s_nop 0
	v_addc_co_u32_e32 v163, vcc, 0, v145, vcc
	v_add_co_u32_e32 v236, vcc, s1, v144
	s_mov_b32 s1, 0x2801000
	s_nop 0
	v_addc_co_u32_e32 v237, vcc, 0, v145, vcc
	v_add_co_u32_e32 v238, vcc, s1, v144
	s_mov_b32 s1, 0x3001000
	s_nop 0
	v_addc_co_u32_e32 v239, vcc, 0, v145, vcc
	v_add_co_u32_e32 v240, vcc, s1, v144
	s_mov_b32 s1, 0x3801000
	s_nop 0
	v_addc_co_u32_e32 v241, vcc, 0, v145, vcc
	v_add_co_u32_e32 v242, vcc, s1, v144
	s_movk_i32 s1, 0xf000
	s_nop 0
	v_addc_co_u32_e32 v243, vcc, 0, v145, vcc
	s_waitcnt vmcnt(0)
	v_pk_add_f32 v[152:153], v[148:149], v[152:153]
	v_pk_add_f32 v[142:143], v[142:143], v[154:155]
	global_load_dwordx4 v[148:151], v[150:151], off offset:3072
	s_waitcnt vmcnt(0)
	v_pk_add_f32 v[142:143], v[142:143], v[150:151]
	v_pk_add_f32 v[150:151], v[152:153], v[148:149]
	global_load_dwordx4 v[146:149], v[146:147], off offset:3072
	s_waitcnt vmcnt(0)
	v_pk_add_f32 v[148:149], v[142:143], v[148:149]
	v_pk_add_f32 v[146:147], v[150:151], v[146:147]
	global_load_dwordx4 v[140:143], v[140:141], off offset:3072
	s_waitcnt vmcnt(0)
	v_pk_add_f32 v[148:149], v[148:149], v[142:143]
	v_pk_add_f32 v[146:147], v[146:147], v[140:141]
	global_load_dwordx4 v[140:143], v[228:229], off
	s_waitcnt vmcnt(0)
	v_pk_fma_f32 v[140:141], v[146:147], v[140:141], v[100:101]
	v_lshl_add_u64 v[146:147], v[156:157], 0, v[164:165]
	v_pk_fma_f32 v[142:143], v[148:149], v[142:143], v[102:103]
	global_load_dwordx4 v[146:149], v[146:147], off
	s_waitcnt vmcnt(0)
	v_pk_add_f32 v[150:151], v[148:149], 0 op_sel_hi:[1,0]
	v_pk_add_f32 v[152:153], v[146:147], 0 op_sel_hi:[1,0]
	global_load_dwordx4 v[146:149], v[158:159], off
	s_waitcnt vmcnt(0)
	v_pk_add_f32 v[150:151], v[150:151], v[148:149]
	v_pk_add_f32 v[152:153], v[152:153], v[146:147]
	global_load_dwordx4 v[146:149], v[160:161], off
	s_waitcnt vmcnt(0)
	v_pk_add_f32 v[150:151], v[150:151], v[148:149]
	v_pk_add_f32 v[152:153], v[152:153], v[146:147]
	global_load_dwordx4 v[146:149], v[162:163], off
	s_waitcnt vmcnt(0)
	v_pk_add_f32 v[150:151], v[150:151], v[148:149]
	v_pk_add_f32 v[152:153], v[152:153], v[146:147]
	global_load_dwordx4 v[146:149], v[236:237], off
	s_waitcnt vmcnt(0)
	v_pk_add_f32 v[150:151], v[150:151], v[148:149]
	v_pk_add_f32 v[152:153], v[152:153], v[146:147]
	global_load_dwordx4 v[146:149], v[238:239], off
	s_waitcnt vmcnt(0)
	v_pk_add_f32 v[150:151], v[150:151], v[148:149]
	v_pk_add_f32 v[152:153], v[152:153], v[146:147]
	global_load_dwordx4 v[146:149], v[240:241], off
	s_waitcnt vmcnt(0)
	v_pk_add_f32 v[148:149], v[150:151], v[148:149]
	v_pk_add_f32 v[150:151], v[152:153], v[146:147]
	global_load_dwordx4 v[144:147], v[242:243], off
	s_waitcnt vmcnt(0)
	v_pk_add_f32 v[148:149], v[148:149], v[146:147]
	v_pk_add_f32 v[150:151], v[150:151], v[144:145]
	global_load_dwordx4 v[144:147], v[230:231], off offset:-4096
	s_waitcnt vmcnt(0)
	v_pk_fma_f32 v[146:147], v[148:149], v[146:147], v[122:123]
	v_lshl_add_u64 v[148:149], v[156:157], 0, v[166:167]
	v_pk_fma_f32 v[144:145], v[150:151], v[144:145], v[120:121]
	global_load_dwordx4 v[148:151], v[148:149], off
	s_waitcnt vmcnt(0)
	v_pk_add_f32 v[152:153], v[150:151], 0 op_sel_hi:[1,0]
	v_pk_add_f32 v[154:155], v[148:149], 0 op_sel_hi:[1,0]
	global_load_dwordx4 v[148:151], v[158:159], off offset:1024
	s_waitcnt vmcnt(0)
	v_pk_add_f32 v[152:153], v[152:153], v[150:151]
	v_pk_add_f32 v[154:155], v[154:155], v[148:149]
	global_load_dwordx4 v[148:151], v[160:161], off offset:1024
	s_waitcnt vmcnt(0)
	v_pk_add_f32 v[152:153], v[152:153], v[150:151]
	v_pk_add_f32 v[154:155], v[154:155], v[148:149]
	global_load_dwordx4 v[148:151], v[162:163], off offset:1024
	s_waitcnt vmcnt(0)
	v_pk_add_f32 v[152:153], v[152:153], v[150:151]
	v_pk_add_f32 v[154:155], v[154:155], v[148:149]
	global_load_dwordx4 v[148:151], v[236:237], off offset:1024
	s_waitcnt vmcnt(0)
	v_pk_add_f32 v[152:153], v[152:153], v[150:151]
	v_pk_add_f32 v[154:155], v[154:155], v[148:149]
	global_load_dwordx4 v[148:151], v[238:239], off offset:1024
	s_waitcnt vmcnt(0)
	v_pk_add_f32 v[152:153], v[152:153], v[150:151]
	v_pk_add_f32 v[154:155], v[154:155], v[148:149]
	global_load_dwordx4 v[148:151], v[240:241], off offset:1024
	s_waitcnt vmcnt(0)
	v_pk_add_f32 v[152:153], v[152:153], v[150:151]
	v_pk_add_f32 v[154:155], v[154:155], v[148:149]
	global_load_dwordx4 v[148:151], v[242:243], off offset:1024
	s_waitcnt vmcnt(0)
	v_pk_add_f32 v[152:153], v[152:153], v[150:151]
	v_pk_add_f32 v[154:155], v[154:155], v[148:149]
	global_load_dwordx4 v[148:151], v[230:231], off offset:-3072
	s_waitcnt vmcnt(0)
	v_pk_fma_f32 v[150:151], v[152:153], v[150:151], v[118:119]
	v_lshl_add_u64 v[152:153], v[156:157], 0, v[168:169]
	v_pk_fma_f32 v[148:149], v[154:155], v[148:149], v[116:117]
	global_load_dwordx4 v[152:155], v[152:153], off
	v_lshl_add_u64 v[156:157], v[156:157], 0, v[170:171]
	global_load_dwordx4 v[248:251], v[158:159], off offset:2048
	s_waitcnt vmcnt(1)
	v_pk_add_f32 v[180:181], v[154:155], 0 op_sel_hi:[1,0]
	v_pk_add_f32 v[182:183], v[152:153], 0 op_sel_hi:[1,0]
	global_load_dwordx4 v[152:155], v[160:161], off offset:2048
	s_waitcnt vmcnt(1)
	v_pk_add_f32 v[180:181], v[180:181], v[250:251]
	v_pk_add_f32 v[182:183], v[182:183], v[248:249]
	global_load_dwordx4 v[248:251], v[162:163], off offset:2048
	s_waitcnt vmcnt(1)
	v_pk_add_f32 v[180:181], v[180:181], v[154:155]
	v_pk_add_f32 v[182:183], v[182:183], v[152:153]
	global_load_dwordx4 v[152:155], v[236:237], off offset:2048
	s_waitcnt vmcnt(1)
	v_pk_add_f32 v[180:181], v[180:181], v[250:251]
	v_pk_add_f32 v[182:183], v[182:183], v[248:249]
	global_load_dwordx4 v[248:251], v[238:239], off offset:2048
	s_waitcnt vmcnt(1)
	v_pk_add_f32 v[180:181], v[180:181], v[154:155]
	v_pk_add_f32 v[182:183], v[182:183], v[152:153]
	global_load_dwordx4 v[152:155], v[240:241], off offset:2048
	s_waitcnt vmcnt(1)
	v_pk_add_f32 v[180:181], v[180:181], v[250:251]
	v_pk_add_f32 v[182:183], v[182:183], v[248:249]
	global_load_dwordx4 v[248:251], v[242:243], off offset:2048
	s_waitcnt vmcnt(1)
	v_pk_add_f32 v[180:181], v[180:181], v[154:155]
	v_pk_add_f32 v[182:183], v[182:183], v[152:153]
	global_load_dwordx4 v[152:155], v[230:231], off offset:-2048
	s_waitcnt vmcnt(1)
	v_pk_add_f32 v[180:181], v[180:181], v[250:251]
	v_pk_add_f32 v[182:183], v[182:183], v[248:249]
	s_waitcnt vmcnt(0)
	v_pk_fma_f32 v[154:155], v[180:181], v[154:155], v[130:131]
	v_pk_fma_f32 v[152:153], v[182:183], v[152:153], v[128:129]
	global_load_dwordx4 v[180:183], v[156:157], off
	global_load_dwordx4 v[248:251], v[158:159], off offset:3072
	s_waitcnt vmcnt(1)
	v_pk_add_f32 v[182:183], v[182:183], 0 op_sel_hi:[1,0]
	v_pk_add_f32 v[180:181], v[180:181], 0 op_sel_hi:[1,0]
	global_load_dwordx4 v[156:159], v[160:161], off offset:3072
	s_waitcnt vmcnt(1)
	v_pk_add_f32 v[182:183], v[182:183], v[250:251]
	v_pk_add_f32 v[180:181], v[180:181], v[248:249]
	global_load_dwordx4 v[248:251], v[162:163], off offset:3072
	s_waitcnt vmcnt(1)
	v_pk_add_f32 v[160:161], v[182:183], v[158:159]
	v_pk_add_f32 v[180:181], v[180:181], v[156:157]
	global_load_dwordx4 v[156:159], v[236:237], off offset:3072
	s_waitcnt vmcnt(1)
	v_pk_add_f32 v[160:161], v[160:161], v[250:251]
	v_pk_add_f32 v[162:163], v[180:181], v[248:249]
	global_load_dwordx4 v[248:251], v[238:239], off offset:3072
	s_waitcnt vmcnt(1)
	v_pk_add_f32 v[160:161], v[160:161], v[158:159]
	v_pk_add_f32 v[162:163], v[162:163], v[156:157]
	global_load_dwordx4 v[156:159], v[240:241], off offset:3072
	s_waitcnt vmcnt(1)
	v_pk_add_f32 v[160:161], v[160:161], v[250:251]
	v_pk_add_f32 v[162:163], v[162:163], v[248:249]
	global_load_dwordx4 v[248:251], v[242:243], off offset:3072
	s_waitcnt vmcnt(1)
	v_pk_add_f32 v[160:161], v[160:161], v[158:159]
	v_pk_add_f32 v[162:163], v[162:163], v[156:157]
	global_load_dwordx4 v[156:159], v[230:231], off offset:-1024
	s_waitcnt vmcnt(1)
	v_pk_add_f32 v[160:161], v[160:161], v[250:251]
	v_pk_add_f32 v[236:237], v[162:163], v[248:249]
	s_waitcnt vmcnt(0)
	v_pk_fma_f32 v[162:163], v[160:161], v[158:159], v[126:127]
	v_pk_fma_f32 v[160:161], v[236:237], v[156:157], v[124:125]
	v_add_co_u32_e32 v156, vcc, s1, v232
	v_ashrrev_i32_e32 v237, 31, v186
	s_nop 0
	v_addc_co_u32_e32 v157, vcc, -1, v233, vcc
	global_store_dwordx4 v[156:157], v[92:95], off offset:-3072
	global_store_dwordx4 v[156:157], v[132:135], off offset:-2048
	global_store_dwordx4 v[156:157], v[136:139], off offset:-1024
	global_store_dwordx4 v[232:233], v[140:143], off offset:-4096
	global_store_dwordx4 v[232:233], v[144:147], off offset:-3072
	global_store_dwordx4 v[232:233], v[148:151], off offset:-2048
	global_store_dwordx4 v[232:233], v[152:155], off offset:-1024
	global_store_dwordx4 v[232:233], v[160:163], off
	v_mov_b64_e32 v[156:157], v[160:161]
	v_mov_b32_e32 v236, v186
	v_mov_b64_e32 v[158:159], v[162:163]
	s_cbranch_execnz .LBB0_88
	s_branch .LBB0_95
